# phase 1: context norm split 4 ways among the workgroups sharing a row block + 4-WG counter rendezvous (release wbl2 / acquire inv), on top of chain v3 and ret_out load hoists
# speedup vs baseline: 1.0046x; 1.0046x over previous
.LBB0_281:
	s_and_b64 vcc, exec, s[6:7]
	s_cbranch_vccz .LBB0_299
	s_lshr_b32 s8, s20, 2
	s_lshl_b32 s6, s8, 20
	s_lshl_b32 s16, s8, 8
	s_add_u32 s0, s22, 0x19b0000
	s_addc_u32 s1, s23, 0
	s_add_u32 s2, s22, 0x19b1000
	v_lshlrev_b32_e32 v118, 4, v160
	s_addc_u32 s3, s23, 0
	s_waitcnt vmcnt(6)
	v_and_b32_e32 v16, 0x3f0, v118
	global_load_dwordx4 v[32:35], v16, s[2:3]
	v_readlane_b32 s36, v240, 8
	v_or_b32_e32 v4, 0x400, v16
	s_waitcnt vmcnt(6)
	v_or_b32_e32 v8, 0x800, v16
	s_waitcnt vmcnt(5)
	v_or_b32_e32 v12, 0xc00, v16
	v_readlane_b32 s40, v240, 12
	v_readlane_b32 s48, v240, 20
	v_readlane_b32 s49, v240, 21
	v_lshrrev_b32_e32 v120, 1, v160
	global_load_dwordx4 v[36:39], v4, s[2:3]
	global_load_dwordx4 v[40:43], v8, s[2:3]
	global_load_dwordx4 v[44:47], v12, s[2:3]
	v_readlane_b32 s41, v240, 13
	global_load_dwordx4 v[98:101], v16, s[48:49]
	global_load_dwordx4 v[102:105], v16, s[48:49] offset:1024
	global_load_dwordx4 v[106:109], v16, s[48:49] offset:2048
	global_load_dwordx4 v[110:113], v16, s[48:49] offset:3072
	v_lshrrev_b32_e32 v116, 3, v160
	v_and_b32_e32 v116, 56, v116
	s_and_b32 s9, s20, 3
	s_lshl_b32 s9, s9, 6
	v_add_u32_e32 v116, s9, v116
	global_load_dwordx4 v[0:3], v16, s[0:1]
	s_nop 0
	global_load_dwordx4 v[4:7], v4, s[0:1]
	s_nop 0
	global_load_dwordx4 v[8:11], v8, s[0:1]
	s_nop 0
	global_load_dwordx4 v[12:15], v12, s[0:1]
	s_add_u32 s0, s40, s6
	v_mov_b32_e32 v115, 0
	v_lshlrev_b32_e32 v114, 12, v116
	s_addc_u32 s1, s41, 0
	v_mov_b32_e32 v17, v115
	v_lshl_add_u64 v[18:19], s[0:1], 0, v[114:115]
	s_movk_i32 s9, 0x1000
	v_lshl_add_u64 v[16:17], v[18:19], 0, v[16:17]
	v_add_co_u32_e32 v18, vcc, s9, v16
	s_movk_i32 s2, 0x2000
	s_nop 0
	v_addc_co_u32_e32 v19, vcc, 0, v17, vcc
	v_add_co_u32_e32 v20, vcc, s2, v16
	s_movk_i32 s3, 0x3000
	s_nop 0
	v_addc_co_u32_e32 v21, vcc, 0, v17, vcc
	global_load_dwordx4 v[88:91], v[16:17], off
	global_load_dwordx4 v[84:87], v[16:17], off offset:1024
	global_load_dwordx4 v[80:83], v[16:17], off offset:2048
	global_load_dwordx4 v[76:79], v[16:17], off offset:3072
	v_add_co_u32_e32 v16, vcc, s3, v16
	v_mbcnt_lo_u32_b32 v96, -1, 0
	s_nop 0
	v_addc_co_u32_e32 v17, vcc, 0, v17, vcc
	global_load_dwordx4 v[72:75], v[18:19], off offset:1024
	global_load_dwordx4 v[68:71], v[18:19], off offset:2048
	global_load_dwordx4 v[92:95], v[20:21], off offset:-4096
	global_load_dwordx4 v[60:63], v[20:21], off
	global_load_dwordx4 v[56:59], v[20:21], off offset:1024
	global_load_dwordx4 v[52:55], v[20:21], off offset:2048
	global_load_dwordx4 v[48:51], v[20:21], off offset:3072
	global_load_dwordx4 v[64:67], v[18:19], off offset:3072
	global_load_dwordx4 v[28:31], v[16:17], off
	global_load_dwordx4 v[24:27], v[16:17], off offset:1024
	s_nop 0
	global_load_dwordx4 v[20:23], v[16:17], off offset:2048
	s_nop 0
	global_load_dwordx4 v[16:19], v[16:17], off offset:3072
	v_mbcnt_hi_u32_b32 v117, -1, v96
	v_and_b32_e32 v96, 64, v117
	v_xor_b32_e32 v121, 32, v117
	v_add_u32_e32 v126, 64, v96
	v_cmp_lt_i32_e32 vcc, v121, v126
	s_mov_b64 s[2:3], 0x30bc000
	s_mov_b32 s10, 0
	v_lshlrev_b32_e32 v119, 2, v160
	v_mov_b32_e32 v127, 0x358637bd
	s_mov_b32 s11, 0x800000
	v_readlane_b32 s37, v240, 9
	v_readlane_b32 s38, v240, 10
	v_readlane_b32 s39, v240, 11
	v_readlane_b32 s42, v240, 14
	v_readlane_b32 s43, v240, 15
	v_readlane_b32 s44, v240, 16
	v_readlane_b32 s45, v240, 17
	v_readlane_b32 s46, v240, 18
	v_readlane_b32 s47, v240, 19
	v_readlane_b32 s50, v240, 22
	v_readlane_b32 s51, v240, 23
	s_waitcnt vmcnt(27)
	v_pk_add_f32 v[32:33], v[32:33], 1.0 op_sel_hi:[1,0]
	v_pk_add_f32 v[34:35], v[34:35], 1.0 op_sel_hi:[1,0]
	s_waitcnt vmcnt(26)
	v_pk_add_f32 v[38:39], v[38:39], 1.0 op_sel_hi:[1,0]
	s_waitcnt vmcnt(23)
	v_pk_mul_f32 v[98:99], v[98:99], v[32:33]
	v_cndmask_b32_e32 v32, v117, v121, vcc
	v_lshlrev_b32_e32 v121, 2, v32
	v_xor_b32_e32 v32, 16, v117
	v_cmp_lt_i32_e32 vcc, v32, v126
	v_pk_mul_f32 v[96:97], v[100:101], v[34:35]
	v_and_b32_e32 v34, 63, v160
	v_cndmask_b32_e32 v32, v117, v32, vcc
	v_lshlrev_b32_e32 v122, 2, v32
	v_xor_b32_e32 v32, 8, v117
	v_cmp_lt_i32_e32 vcc, v32, v126
	v_add_u32_e32 v33, s16, v116
	v_pk_add_f32 v[42:43], v[42:43], 1.0 op_sel_hi:[1,0]
	v_cndmask_b32_e32 v32, v117, v32, vcc
	v_lshlrev_b32_e32 v123, 2, v32
	v_xor_b32_e32 v32, 4, v117
	v_cmp_lt_i32_e32 vcc, v32, v126
	v_pk_add_f32 v[46:47], v[46:47], 1.0 op_sel_hi:[1,0]
	v_lshl_or_b32 v114, v34, 4, v114
	v_cndmask_b32_e32 v32, v117, v32, vcc
	v_lshlrev_b32_e32 v124, 2, v32
	v_xor_b32_e32 v32, 2, v117
	v_cmp_lt_i32_e32 vcc, v32, v126
	v_pk_add_f32 v[36:37], v[36:37], 1.0 op_sel_hi:[1,0]
	v_pk_add_f32 v[40:41], v[40:41], 1.0 op_sel_hi:[1,0]
	v_cndmask_b32_e32 v32, v117, v32, vcc
	v_lshlrev_b32_e32 v125, 2, v32
	v_xor_b32_e32 v32, 1, v117
	v_cmp_lt_i32_e32 vcc, v32, v126
	v_pk_add_f32 v[44:45], v[44:45], 1.0 op_sel_hi:[1,0]
	s_waitcnt vmcnt(22)
	v_pk_mul_f32 v[100:101], v[104:105], v[38:39]
	v_cndmask_b32_e32 v32, v117, v32, vcc
	v_lshlrev_b32_e32 v126, 2, v32
	v_lshlrev_b32_e32 v32, 3, v34
	v_lshl_or_b32 v32, v33, 11, v32
	v_add_u32_e32 v32, 0x4000000, v32
	v_mov_b32_e32 v33, v115
	v_lshl_add_u64 v[32:33], s[22:23], 0, v[32:33]
	s_waitcnt vmcnt(21)
	v_pk_mul_f32 v[104:105], v[108:109], v[42:43]
	s_waitcnt vmcnt(20)
	v_pk_mul_f32 v[108:109], v[112:113], v[46:47]
	v_lshl_add_u64 v[112:113], v[32:33], 0, s[2:3]
	v_lshl_add_u64 v[32:33], s[0:1], 0, v[114:115]
	s_mov_b64 s[0:1], 0x7c00
	v_pk_mul_f32 v[102:103], v[102:103], v[36:37]
	v_pk_mul_f32 v[106:107], v[106:107], v[40:41]
	v_pk_mul_f32 v[110:111], v[110:111], v[44:45]
	v_lshl_add_u64 v[114:115], v[32:33], 0, s[0:1]
	s_waitcnt vmcnt(12)
	v_mov_b64_e32 v[32:33], v[76:77]
	v_mov_b64_e32 v[36:37], v[80:81]
	v_mov_b64_e32 v[40:41], v[84:85]
	v_mov_b64_e32 v[44:45], v[88:89]
	s_mov_b64 s[0:1], 0x2000
	s_mov_b64 s[2:3], 0x4000
	v_mov_b64_e32 v[34:35], v[78:79]
	v_mov_b64_e32 v[38:39], v[82:83]
	v_mov_b64_e32 v[42:43], v[86:87]
	v_mov_b64_e32 v[46:47], v[90:91]
	s_branch .LBB0_284

.LBB0_284:
	v_mov_b32_e32 v128, v85
	v_mov_b32_e32 v129, v89
	v_mov_b32_e32 v116, v84
	v_mov_b32_e32 v117, v88
	v_pk_mul_f32 v[128:129], v[128:129], v[128:129]
	v_mov_b32_e32 v130, v77
	v_pk_fma_f32 v[116:117], v[116:117], v[116:117], v[128:129]
	v_mov_b32_e32 v128, v86
	v_mov_b32_e32 v129, v90
	v_pk_fma_f32 v[116:117], v[128:129], v[128:129], v[116:117]
	v_mov_b32_e32 v128, v87
	v_mov_b32_e32 v129, v91
	v_mov_b32_e32 v131, v81
	v_pk_fma_f32 v[116:117], v[128:129], v[128:129], v[116:117]
	v_mov_b32_e32 v128, v76
	v_mov_b32_e32 v129, v80
	v_pk_mul_f32 v[130:131], v[130:131], v[130:131]
	v_add_f32_e32 v116, v116, v117
	v_pk_fma_f32 v[128:129], v[128:129], v[128:129], v[130:131]
	v_mov_b32_e32 v130, v78
	v_mov_b32_e32 v131, v82
	v_pk_fma_f32 v[128:129], v[130:131], v[130:131], v[128:129]
	v_mov_b32_e32 v130, v79
	v_mov_b32_e32 v131, v83
	v_pk_fma_f32 v[128:129], v[130:131], v[130:131], v[128:129]
	s_cmp_gt_u32 s10, 3
	v_add_f32_e32 v116, v129, v116
	v_add_f32_e32 v116, v128, v116
	ds_bpermute_b32 v117, v121, v116
	s_cselect_b64 s[6:7], -1, 0
	s_cmp_lt_u32 s10, 4
	s_waitcnt lgkmcnt(0)
	v_add_f32_e32 v116, v116, v117
	ds_bpermute_b32 v117, v122, v116
	s_waitcnt lgkmcnt(0)
	v_add_f32_e32 v116, v116, v117
	ds_bpermute_b32 v117, v123, v116
	s_waitcnt lgkmcnt(0)
	v_add_f32_e32 v116, v116, v117
	ds_bpermute_b32 v117, v124, v116
	s_waitcnt lgkmcnt(0)
	v_add_f32_e32 v116, v116, v117
	ds_bpermute_b32 v117, v125, v116
	s_waitcnt lgkmcnt(0)
	v_add_f32_e32 v116, v116, v117
	ds_bpermute_b32 v117, v126, v116
	s_cbranch_scc0 .LBB0_286
	v_add_co_u32_e32 v32, vcc, 0xffffd000, v114
	s_nop 1
	v_addc_co_u32_e32 v33, vcc, -1, v115, vcc
	global_load_dwordx4 v[44:47], v[32:33], off offset:-3072
	global_load_dwordx4 v[40:43], v[32:33], off offset:-2048
	global_load_dwordx4 v[36:39], v[32:33], off offset:-1024
	s_nop 0
	global_load_dwordx4 v[32:35], v[32:33], off
.LBB0_286:
	s_waitcnt lgkmcnt(0)
	v_add_f32_e32 v116, v116, v117
	v_fmamk_f32 v116, v116, 0x3a800000, v127
	v_mul_f32_e32 v117, 0x4b800000, v116
	v_cmp_gt_f32_e32 vcc, s11, v116
	s_waitcnt vmcnt(11)
	v_mov_b32_e32 v128, v73
	s_waitcnt vmcnt(9)
	v_mov_b32_e32 v129, v93
	v_cndmask_b32_e32 v116, v116, v117, vcc
	v_rsq_f32_e32 v116, v116
	v_pk_mul_f32 v[128:129], v[128:129], v[128:129]
	s_waitcnt vmcnt(4)
	v_mov_b32_e32 v130, v65
	v_mov_b32_e32 v131, v69
	v_mul_f32_e32 v117, 0x45800000, v116
	v_cndmask_b32_e32 v116, v116, v117, vcc
	v_pk_mul_f32 v[88:89], v[88:89], v[116:117] op_sel_hi:[1,0]
	v_pk_mul_f32 v[90:91], v[90:91], v[116:117] op_sel_hi:[1,0]
	v_pk_fma_f32 v[88:89], v[98:99], v[88:89], v[0:1]
	v_pk_fma_f32 v[90:91], v[96:97], v[90:91], v[2:3]
	v_cvt_pk_bf16_f32 v88, v88, v89
	v_cvt_pk_bf16_f32 v89, v90, v91
	v_mov_b32_e32 v90, v72
	v_mov_b32_e32 v91, v92
	v_pk_fma_f32 v[90:91], v[90:91], v[90:91], v[128:129]
	v_mov_b32_e32 v128, v74
	v_mov_b32_e32 v129, v94
	v_pk_fma_f32 v[90:91], v[128:129], v[128:129], v[90:91]
	v_mov_b32_e32 v128, v75
	v_mov_b32_e32 v129, v95
	v_pk_fma_f32 v[90:91], v[128:129], v[128:129], v[90:91]
	v_mov_b32_e32 v128, v64
	v_mov_b32_e32 v129, v68
	v_pk_mul_f32 v[130:131], v[130:131], v[130:131]
	v_add_f32_e32 v90, v90, v91
	v_pk_fma_f32 v[128:129], v[128:129], v[128:129], v[130:131]
	v_mov_b32_e32 v130, v66
	v_mov_b32_e32 v131, v70
	v_pk_fma_f32 v[128:129], v[130:131], v[130:131], v[128:129]
	v_mov_b32_e32 v130, v67
	v_mov_b32_e32 v131, v71
	v_pk_fma_f32 v[128:129], v[130:131], v[130:131], v[128:129]
	v_pk_mul_f32 v[84:85], v[84:85], v[116:117] op_sel_hi:[1,0]
	v_add_f32_e32 v90, v129, v90
	v_add_f32_e32 v90, v128, v90
	ds_bpermute_b32 v91, v121, v90
	v_pk_mul_f32 v[86:87], v[86:87], v[116:117] op_sel_hi:[1,0]
	v_pk_fma_f32 v[84:85], v[102:103], v[84:85], v[4:5]
	v_pk_fma_f32 v[86:87], v[100:101], v[86:87], v[6:7]
	v_cvt_pk_bf16_f32 v84, v84, v85
	v_cvt_pk_bf16_f32 v85, v86, v87
	s_waitcnt lgkmcnt(0)
	v_add_f32_e32 v86, v90, v91
	ds_bpermute_b32 v87, v122, v86
	v_pk_mul_f32 v[80:81], v[80:81], v[116:117] op_sel_hi:[1,0]
	v_pk_mul_f32 v[82:83], v[82:83], v[116:117] op_sel_hi:[1,0]
	v_pk_fma_f32 v[80:81], v[106:107], v[80:81], v[8:9]
	v_pk_fma_f32 v[82:83], v[104:105], v[82:83], v[10:11]
	s_waitcnt lgkmcnt(0)
	v_add_f32_e32 v86, v86, v87
	ds_bpermute_b32 v87, v123, v86
	v_cvt_pk_bf16_f32 v80, v80, v81
	v_cvt_pk_bf16_f32 v81, v82, v83
	v_pk_mul_f32 v[76:77], v[76:77], v[116:117] op_sel_hi:[1,0]
	v_pk_mul_f32 v[78:79], v[78:79], v[116:117] op_sel_hi:[1,0]
	s_waitcnt lgkmcnt(0)
	v_add_f32_e32 v82, v86, v87
	ds_bpermute_b32 v83, v124, v82
	v_pk_fma_f32 v[78:79], v[108:109], v[78:79], v[14:15]
	v_pk_fma_f32 v[76:77], v[110:111], v[76:77], v[12:13]
	s_cmp_gt_u32 s10, 2
	v_cvt_pk_bf16_f32 v76, v76, v77
	v_cvt_pk_bf16_f32 v77, v78, v79
	s_waitcnt lgkmcnt(0)
	v_add_f32_e32 v78, v82, v83
	ds_bpermute_b32 v79, v125, v78
	global_store_dwordx2 v[112:113], v[88:89], off
	global_store_dwordx2 v[112:113], v[84:85], off offset:512
	global_store_dwordx2 v[112:113], v[80:81], off offset:1024
	global_store_dwordx2 v[112:113], v[76:77], off offset:1536
	v_mov_b64_e32 v[90:91], v[66:67]
	v_mov_b64_e32 v[86:87], v[70:71]
	v_mov_b64_e32 v[82:83], v[74:75]
	s_waitcnt lgkmcnt(0)
	v_add_f32_e32 v116, v78, v79
	ds_bpermute_b32 v117, v126, v116
	v_mov_b64_e32 v[76:77], v[92:93]
	v_mov_b64_e32 v[88:89], v[64:65]
	v_mov_b64_e32 v[84:85], v[68:69]
	v_mov_b64_e32 v[80:81], v[72:73]
	v_mov_b64_e32 v[78:79], v[94:95]
	s_cbranch_scc1 .LBB0_288
	v_add_co_u32_e32 v88, vcc, 0xffffe000, v114
	s_nop 1
	v_addc_co_u32_e32 v89, vcc, -1, v115, vcc
	global_load_dwordx4 v[76:79], v[88:89], off offset:-3072
	global_load_dwordx4 v[80:83], v[88:89], off offset:-2048
	global_load_dwordx4 v[84:87], v[88:89], off offset:-1024
	s_nop 0
	global_load_dwordx4 v[88:91], v[88:89], off
.LBB0_288:
	s_waitcnt lgkmcnt(0)
	v_add_f32_e32 v116, v116, v117
	v_fmamk_f32 v116, v116, 0x3a800000, v127
	v_mul_f32_e32 v117, 0x4b800000, v116
	v_cmp_gt_f32_e32 vcc, s11, v116
	v_mov_b32_e32 v128, v57
	v_mov_b32_e32 v129, v61
	v_cndmask_b32_e32 v116, v116, v117, vcc
	v_rsq_f32_e32 v116, v116
	v_pk_mul_f32 v[128:129], v[128:129], v[128:129]
	v_mov_b32_e32 v130, v49
	v_mov_b32_e32 v131, v53
	v_mul_f32_e32 v117, 0x45800000, v116
	v_cndmask_b32_e32 v116, v116, v117, vcc
	v_pk_mul_f32 v[92:93], v[92:93], v[116:117] op_sel_hi:[1,0]
	v_pk_mul_f32 v[94:95], v[94:95], v[116:117] op_sel_hi:[1,0]
	v_pk_fma_f32 v[92:93], v[98:99], v[92:93], v[0:1]
	v_pk_fma_f32 v[94:95], v[96:97], v[94:95], v[2:3]
	v_cvt_pk_bf16_f32 v92, v92, v93
	v_cvt_pk_bf16_f32 v93, v94, v95
	v_mov_b32_e32 v94, v56
	v_mov_b32_e32 v95, v60
	v_pk_fma_f32 v[94:95], v[94:95], v[94:95], v[128:129]
	v_mov_b32_e32 v128, v58
	v_mov_b32_e32 v129, v62
	v_pk_fma_f32 v[94:95], v[128:129], v[128:129], v[94:95]
	v_mov_b32_e32 v128, v59
	v_mov_b32_e32 v129, v63
	v_pk_fma_f32 v[94:95], v[128:129], v[128:129], v[94:95]
	v_mov_b32_e32 v128, v48
	v_mov_b32_e32 v129, v52
	v_pk_mul_f32 v[130:131], v[130:131], v[130:131]
	v_add_f32_e32 v94, v94, v95
	v_pk_fma_f32 v[128:129], v[128:129], v[128:129], v[130:131]
	v_mov_b32_e32 v130, v50
	v_mov_b32_e32 v131, v54
	v_pk_fma_f32 v[128:129], v[130:131], v[130:131], v[128:129]
	v_mov_b32_e32 v130, v51
	v_mov_b32_e32 v131, v55
	v_pk_fma_f32 v[128:129], v[130:131], v[130:131], v[128:129]
	v_pk_mul_f32 v[72:73], v[72:73], v[116:117] op_sel_hi:[1,0]
	v_add_f32_e32 v94, v129, v94
	v_add_f32_e32 v94, v128, v94
	ds_bpermute_b32 v95, v121, v94
	v_pk_mul_f32 v[74:75], v[74:75], v[116:117] op_sel_hi:[1,0]
	v_pk_fma_f32 v[72:73], v[102:103], v[72:73], v[4:5]
	v_pk_fma_f32 v[74:75], v[100:101], v[74:75], v[6:7]
	v_cvt_pk_bf16_f32 v72, v72, v73
	v_cvt_pk_bf16_f32 v73, v74, v75
	s_waitcnt lgkmcnt(0)
	v_add_f32_e32 v74, v94, v95
	ds_bpermute_b32 v75, v122, v74
	v_pk_mul_f32 v[68:69], v[68:69], v[116:117] op_sel_hi:[1,0]
	v_pk_mul_f32 v[70:71], v[70:71], v[116:117] op_sel_hi:[1,0]
	v_pk_fma_f32 v[68:69], v[106:107], v[68:69], v[8:9]
	v_pk_fma_f32 v[70:71], v[104:105], v[70:71], v[10:11]
	s_waitcnt lgkmcnt(0)
	v_add_f32_e32 v74, v74, v75
	ds_bpermute_b32 v75, v123, v74
	v_cvt_pk_bf16_f32 v68, v68, v69
	v_cvt_pk_bf16_f32 v69, v70, v71
	v_pk_mul_f32 v[64:65], v[64:65], v[116:117] op_sel_hi:[1,0]
	v_pk_mul_f32 v[66:67], v[66:67], v[116:117] op_sel_hi:[1,0]
	s_waitcnt lgkmcnt(0)
	v_add_f32_e32 v70, v74, v75
	ds_bpermute_b32 v71, v124, v70
	v_pk_fma_f32 v[66:67], v[108:109], v[66:67], v[14:15]
	v_pk_fma_f32 v[64:65], v[110:111], v[64:65], v[12:13]
	s_cmp_gt_u32 s10, 1
	v_cvt_pk_bf16_f32 v64, v64, v65
	v_cvt_pk_bf16_f32 v65, v66, v67
	s_waitcnt lgkmcnt(0)
	v_add_f32_e32 v66, v70, v71
	ds_bpermute_b32 v67, v125, v66
	global_store_dwordx2 v[112:113], v[92:93], off offset:2048
	global_store_dwordx2 v[112:113], v[72:73], off offset:2560
	global_store_dwordx2 v[112:113], v[68:69], off offset:3072
	global_store_dwordx2 v[112:113], v[64:65], off offset:3584
	v_mov_b64_e32 v[94:95], v[50:51]
	v_mov_b64_e32 v[74:75], v[54:55]
	v_mov_b64_e32 v[70:71], v[58:59]
	s_waitcnt lgkmcnt(0)
	v_add_f32_e32 v116, v66, v67
	ds_bpermute_b32 v117, v126, v116
	v_mov_b64_e32 v[66:67], v[62:63]
	v_mov_b64_e32 v[92:93], v[48:49]
	v_mov_b64_e32 v[72:73], v[52:53]
	v_mov_b64_e32 v[68:69], v[56:57]
	v_mov_b64_e32 v[64:65], v[60:61]
	s_cbranch_scc1 .LBB0_290
	v_add_co_u32_e32 v72, vcc, 0xfffff000, v114
	s_nop 1
	v_addc_co_u32_e32 v73, vcc, -1, v115, vcc
	global_load_dwordx4 v[64:67], v[72:73], off offset:-3072
	global_load_dwordx4 v[68:71], v[72:73], off offset:-2048
	s_nop 0
	global_load_dwordx4 v[72:75], v[72:73], off offset:-1024
	s_nop 0
	global_load_dwordx4 v[92:95], v[114:115], off offset:-4096
.LBB0_290:
	s_waitcnt lgkmcnt(0)
	v_add_f32_e32 v116, v116, v117
	v_fmamk_f32 v116, v116, 0x3a800000, v127
	v_mul_f32_e32 v117, 0x4b800000, v116
	v_cmp_gt_f32_e32 vcc, s11, v116
	s_waitcnt vmcnt(8)
	v_mov_b32_e32 v128, v17
	v_mov_b32_e32 v129, v21
	v_cndmask_b32_e32 v116, v116, v117, vcc
	v_rsq_f32_e32 v116, v116
	v_pk_mul_f32 v[128:129], v[128:129], v[128:129]
	s_cmp_gt_u32 s10, 0
	v_mul_f32_e32 v117, 0x45800000, v116
	v_cndmask_b32_e32 v116, v116, v117, vcc
	v_pk_mul_f32 v[60:61], v[60:61], v[116:117] op_sel_hi:[1,0]
	v_pk_mul_f32 v[62:63], v[62:63], v[116:117] op_sel_hi:[1,0]
	v_pk_fma_f32 v[60:61], v[98:99], v[60:61], v[0:1]
	v_pk_fma_f32 v[62:63], v[96:97], v[62:63], v[2:3]
	v_pk_mul_f32 v[56:57], v[56:57], v[116:117] op_sel_hi:[1,0]
	v_pk_mul_f32 v[58:59], v[58:59], v[116:117] op_sel_hi:[1,0]
	v_cvt_pk_bf16_f32 v60, v60, v61
	v_cvt_pk_bf16_f32 v61, v62, v63
	v_pk_fma_f32 v[58:59], v[100:101], v[58:59], v[6:7]
	v_pk_fma_f32 v[56:57], v[102:103], v[56:57], v[4:5]
	v_mov_b32_e32 v62, v25
	v_mov_b32_e32 v63, v29
	v_cvt_pk_bf16_f32 v56, v56, v57
	v_cvt_pk_bf16_f32 v57, v58, v59
	v_mov_b32_e32 v58, v24
	v_mov_b32_e32 v59, v28
	v_pk_mul_f32 v[62:63], v[62:63], v[62:63]
	v_pk_mul_f32 v[52:53], v[52:53], v[116:117] op_sel_hi:[1,0]
	v_pk_fma_f32 v[58:59], v[58:59], v[58:59], v[62:63]
	v_mov_b32_e32 v62, v26
	v_mov_b32_e32 v63, v30
	v_pk_fma_f32 v[58:59], v[62:63], v[62:63], v[58:59]
	v_mov_b32_e32 v62, v27
	v_mov_b32_e32 v63, v31
	v_pk_fma_f32 v[58:59], v[62:63], v[62:63], v[58:59]
	v_mov_b32_e32 v62, v16
	v_mov_b32_e32 v63, v20
	v_pk_fma_f32 v[62:63], v[62:63], v[62:63], v[128:129]
	v_mov_b32_e32 v128, v18
	v_mov_b32_e32 v129, v22
	v_pk_fma_f32 v[62:63], v[128:129], v[128:129], v[62:63]
	v_mov_b32_e32 v128, v19
	v_mov_b32_e32 v129, v23
	v_pk_fma_f32 v[62:63], v[128:129], v[128:129], v[62:63]
	v_add_f32_e32 v58, v58, v59
	v_add_f32_e32 v58, v63, v58
	v_add_f32_e32 v58, v62, v58
	ds_bpermute_b32 v59, v121, v58
	v_pk_mul_f32 v[54:55], v[54:55], v[116:117] op_sel_hi:[1,0]
	v_pk_fma_f32 v[52:53], v[106:107], v[52:53], v[8:9]
	v_pk_fma_f32 v[54:55], v[104:105], v[54:55], v[10:11]
	v_cvt_pk_bf16_f32 v52, v52, v53
	s_waitcnt lgkmcnt(0)
	v_add_f32_e32 v58, v58, v59
	ds_bpermute_b32 v59, v122, v58
	v_cvt_pk_bf16_f32 v53, v54, v55
	v_pk_mul_f32 v[48:49], v[48:49], v[116:117] op_sel_hi:[1,0]
	v_pk_mul_f32 v[50:51], v[50:51], v[116:117] op_sel_hi:[1,0]
	v_pk_fma_f32 v[48:49], v[110:111], v[48:49], v[12:13]
	s_waitcnt lgkmcnt(0)
	v_add_f32_e32 v54, v58, v59
	ds_bpermute_b32 v55, v123, v54
	v_pk_fma_f32 v[50:51], v[108:109], v[50:51], v[14:15]
	v_cvt_pk_bf16_f32 v48, v48, v49
	v_cvt_pk_bf16_f32 v49, v50, v51
	v_add_co_u32_e32 v116, vcc, s9, v112
	s_waitcnt lgkmcnt(0)
	v_add_f32_e32 v50, v54, v55
	ds_bpermute_b32 v51, v124, v50
	v_addc_co_u32_e32 v117, vcc, 0, v113, vcc
	global_store_dwordx2 v[116:117], v[60:61], off
	global_store_dwordx2 v[116:117], v[56:57], off offset:512
	global_store_dwordx2 v[116:117], v[52:53], off offset:1024
	global_store_dwordx2 v[116:117], v[48:49], off offset:1536
	v_mov_b64_e32 v[62:63], v[18:19]
	s_waitcnt lgkmcnt(0)
	v_add_f32_e32 v50, v50, v51
	ds_bpermute_b32 v51, v125, v50
	v_mov_b64_e32 v[58:59], v[22:23]
	v_mov_b64_e32 v[54:55], v[26:27]
	v_mov_b64_e32 v[60:61], v[16:17]
	v_mov_b64_e32 v[56:57], v[20:21]
	s_waitcnt lgkmcnt(0)
	v_add_f32_e32 v128, v50, v51
	ds_bpermute_b32 v129, v126, v128
	v_mov_b64_e32 v[50:51], v[30:31]
	v_mov_b64_e32 v[52:53], v[24:25]
	v_mov_b64_e32 v[48:49], v[28:29]
	s_cbranch_scc1 .LBB0_283
	global_load_dwordx4 v[48:51], v[114:115], off offset:-3072
	global_load_dwordx4 v[52:55], v[114:115], off offset:-2048
	global_load_dwordx4 v[56:59], v[114:115], off offset:-1024
	global_load_dwordx4 v[60:63], v[114:115], off
	s_branch .LBB0_283
.LBB0_292:
	v_lshrrev_b32_e32 v1, 5, v160
	v_and_b32_e32 v140, 24, v120
	v_and_b32_e32 v1, 4, v1
	v_bfe_u32 v2, v160, 2, 2
	v_readfirstlane_b32 s17, v160
	v_and_b32_e32 v0, 32, v160
	v_bfe_u32 v10, v160, 2, 4
	v_or3_b32 v1, v1, v2, v140
	v_lshrrev_b32_e32 v2, 3, v160
	s_movk_i32 s0, 0x70
	s_and_b32 s24, s20, 3
	v_bitop3_b32 v8, v118, v0, 48 bitop3:0x6c
	v_and_b32_e32 v9, 64, v160
	v_and_or_b32 v3, v2, s0, v10
	s_movk_i32 s0, 0x60
	s_lshr_b32 s7, s17, 6
	s_lshr_b32 s6, s17, 8
	v_or_b32_e32 v0, v8, v9
	v_and_or_b32 v2, v2, s0, v1
	v_add_u32_e32 v11, 0x2000, v118
	s_lshl_b32 s12, s7, 10
	s_lshl_b32 s8, s8, 19
	s_lshl_b32 s10, s24, 19
	v_lshl_or_b32 v130, v2, 11, v0
	v_lshrrev_b32_e32 v2, 7, v11
	s_movk_i32 s0, 0xf0
	s_add_u32 s9, s22, s10
	v_lshl_or_b32 v128, v3, 11, v0
	v_and_or_b32 v3, v2, s0, v10
	s_movk_i32 s0, 0xe0
	s_addc_u32 s11, s23, 0
	v_and_or_b32 v1, v2, s0, v1
	s_add_u32 s0, s9, 0x100000
	s_addc_u32 s1, s11, 0
	s_add_i32 s25, s12, 0
	s_waitcnt vmcnt(0)
	s_barrier
	v_readfirstlane_b32 s98, v160
	s_nop 3
	s_lshr_b32 s98, s98, 6
	s_cmp_lg_u32 s98, 0
	s_cbranch_scc1 .Lctx_sync_done
	s_mov_b64 exec, 1
	buffer_wbl2 sc1
	s_waitcnt vmcnt(0)
	s_lshr_b32 s98, s20, 2
	s_lshl_b32 s98, s98, 6
	v_mov_b32_e32 v241, s98
	v_mov_b32_e32 v242, 1
	v_mov_b32_e32 v244, 0
	s_add_u32 s98, s22, 0x2cb8000
	s_addc_u32 s99, s23, 0
	global_atomic_add v241, v242, s[98:99]
.Lctx_sync_spin:
	s_sleep 1
	global_load_dword v243, v241, s[98:99] sc1
	v_add_u32_e32 v244, 1, v244
	s_waitcnt vmcnt(0)
	v_cmp_gt_u32_e32 vcc, 4, v243
	s_cbranch_vccz .Lctx_sync_ok
	v_cmp_gt_u32_e32 vcc, 0x1000, v244
	s_cbranch_vccnz .Lctx_sync_spin
.Lctx_sync_ok:
	s_mov_b64 exec, -1
.Lctx_sync_done:
	s_barrier
	s_waitcnt vmcnt(0)
	buffer_inv sc1
	s_waitcnt vmcnt(0)
	s_add_i32 m0, s25, 0x10000
	v_lshl_or_b32 v134, v1, 11, v0
	global_load_lds_dwordx4 v130, s[0:1]
	s_add_i32 m0, s25, 0x12000
	s_add_u32 s13, s22, s8
	s_addc_u32 s27, s23, 0
	s_add_u32 s2, s13, 0x70bc000
	global_load_lds_dwordx4 v134, s[0:1]
	s_addc_u32 s3, s27, 0
	s_mov_b32 m0, s25
	s_add_i32 s26, s25, 0x2000
	v_lshl_or_b32 v132, v3, 11, v0
	global_load_lds_dwordx4 v128, s[2:3]
	s_mov_b32 m0, s26
	s_add_u32 s14, s9, 0x140000
	global_load_lds_dwordx4 v132, s[2:3]
	s_addc_u32 s15, s11, 0
	s_add_i32 m0, s25, 0x14000
	v_mov_b32_e32 v131, 0
	global_load_lds_dwordx4 v130, s[14:15]
	s_add_i32 m0, s25, 0x16000
	v_mov_b32_e32 v135, v131
	global_load_lds_dwordx4 v134, s[14:15]
	s_add_u32 s14, s13, 0x70fc000
	s_addc_u32 s15, s27, 0
	s_add_i32 s27, s25, 0x4000
	s_mov_b32 m0, s27
	s_add_i32 s28, s25, 0x6000
	global_load_lds_dwordx4 v128, s[14:15]
	s_mov_b32 m0, s28
	v_mov_b32_e32 v129, v131
	global_load_lds_dwordx4 v132, s[14:15]
	v_mov_b32_e32 v133, v131
	v_lshl_add_u64 v[6:7], s[0:1], 0, v[130:131]
	v_lshl_add_u64 v[4:5], s[0:1], 0, v[134:135]
	v_lshl_add_u64 v[2:3], s[2:3], 0, v[128:129]
	s_cmp_lg_u32 s6, 1
	v_lshl_add_u64 v[0:1], s[2:3], 0, v[132:133]
	s_cbranch_scc1 .LBB0_294
	s_barrier
